# adds: diff loop K and V fragment LDS read addresses computed one iteration ahead in the MFMA hazard shadow (6 fewer VALU in the MFMA half, nop shortened)
# speedup vs baseline: 1.0524x; 1.0123x over previous
; #define VLOAD(dst, sbv, q) do { _Pragma("unroll") for (int d_ = 0; d_ < 4; ++d_) dst[d_] = *(const lds_bf16x8*)((sbv) + vo[q] + d_ * 4096); } while (0)
; DI void diff_unit(KP p, int l, int b, int h, int qb, int isctx, float lamv, float lam_init, char* ldsc) {
;     ...
;   bf16x8 P[4];
;   {
;     f32x16 st[2];
;     qk_tile(qf, L + comp * 8192, ko, st);
;     m = tile_max(st);
;     lsum = exp_pack(st, m, P);
;   }
;   int stg = 0;
;   bool need = false; float alpha = 1.f;
;   if (w >= 4) __builtin_amdgcn_s_setprio(1);
;   bf16x8 vA[4], vB[4];
;   VLOAD(vA, L + 16384, 0); VLOAD(vB, L + 16384, 1);
.LBB0_470:
	v_and_b32_e32 v133, 63, v38
	v_max_f32_e32 v38, v43, v43
	v_max_f32_e32 v42, v42, v42
	v_max_f32_e32 v153, v42, v38
	v_sub_f32_e32 v252, 0, v153
	v_mov_b32_e32 v253, v252
	v_fma_f32 v2, v2, 1.0, -v153
	v_fma_f32 v3, v3, 1.0, -v153
	v_exp_f32_e32 v2, v2
	v_exp_f32_e32 v3, v3
	v_fma_f32 v10, v10, 1.0, -v153
	v_exp_f32_e32 v10, v10
	v_fma_f32 v11, v11, 1.0, -v153
	v_fma_f32 v4, v4, 1.0, -v153
	v_exp_f32_e32 v11, v11
	v_fma_f32 v12, v12, 1.0, -v153
	v_exp_f32_e32 v4, v4
	v_fma_f32 v5, v5, 1.0, -v153
	v_exp_f32_e32 v12, v12
	v_fma_f32 v13, v13, 1.0, -v153
	v_exp_f32_e32 v5, v5
	v_fma_f32 v6, v6, 1.0, -v153
	v_cvt_pk_bf16_f32 v66, v2, v3
	v_exp_f32_e32 v13, v13
	v_fma_f32 v14, v14, 1.0, -v153
	v_add_f32_e32 v2, 0, v2
	v_exp_f32_e32 v6, v6
	v_fma_f32 v7, v7, 1.0, -v153
	v_exp_f32_e32 v14, v14
	v_fma_f32 v15, v15, 1.0, -v153
	v_add_f32_e32 v2, v3, v2
	v_add_f32_e32 v3, 0, v10
	v_exp_f32_e32 v7, v7
	v_fma_f32 v8, v8, 1.0, -v153
	v_exp_f32_e32 v15, v15
	v_fma_f32 v16, v16, 1.0, -v153
	v_add_f32_e32 v3, v11, v3
	v_exp_f32_e32 v8, v8
	v_fma_f32 v9, v9, 1.0, -v153
	v_exp_f32_e32 v16, v16
	v_fma_f32 v17, v17, 1.0, -v153
	v_add_f32_e32 v2, v4, v2
	v_add_f32_e32 v3, v12, v3
	v_exp_f32_e32 v9, v9
	v_exp_f32_e32 v17, v17
	v_fma_f32 v18, v18, 1.0, -v153
	v_fma_f32 v26, v26, 1.0, -v153
	v_add_f32_e32 v2, v5, v2
	v_add_f32_e32 v3, v13, v3
	v_exp_f32_e32 v18, v18
	v_fma_f32 v19, v19, 1.0, -v153
	v_exp_f32_e32 v26, v26
	v_fma_f32 v27, v27, 1.0, -v153
	v_add_f32_e32 v2, v6, v2
	v_add_f32_e32 v3, v14, v3
	v_exp_f32_e32 v19, v19
	v_fma_f32 v20, v20, 1.0, -v153
	v_exp_f32_e32 v27, v27
	v_fma_f32 v28, v28, 1.0, -v153
	v_add_f32_e32 v2, v7, v2
	v_add_f32_e32 v3, v15, v3
	v_exp_f32_e32 v20, v20
	v_fma_f32 v21, v21, 1.0, -v153
	v_exp_f32_e32 v28, v28
	v_fma_f32 v29, v29, 1.0, -v153
	v_add_f32_e32 v2, v8, v2
	v_add_f32_e32 v3, v16, v3
	v_exp_f32_e32 v21, v21
	v_fma_f32 v22, v22, 1.0, -v153
	v_exp_f32_e32 v29, v29
	v_fma_f32 v30, v30, 1.0, -v153
	v_add_f32_e32 v2, v9, v2
	v_add_f32_e32 v3, v17, v3
	v_cvt_pk_bf16_f32 v67, v4, v5
	v_exp_f32_e32 v22, v22
	v_fma_f32 v23, v23, 1.0, -v153
	v_exp_f32_e32 v30, v30
	v_fma_f32 v31, v31, 1.0, -v153
	v_add_f32_e32 v2, v2, v3
	v_add_f32_e32 v3, 0, v18
	v_add_f32_e32 v4, 0, v26
	v_exp_f32_e32 v23, v23
	v_fma_f32 v24, v24, 1.0, -v153
	v_exp_f32_e32 v31, v31
	v_fma_f32 v32, v32, 1.0, -v153
	v_add_f32_e32 v3, v19, v3
	v_add_f32_e32 v4, v27, v4
	v_exp_f32_e32 v24, v24
	v_fma_f32 v25, v25, 1.0, -v153
	v_exp_f32_e32 v32, v32
	v_fma_f32 v33, v33, 1.0, -v153
	v_add_f32_e32 v3, v20, v3
	v_add_f32_e32 v4, v28, v4
	v_exp_f32_e32 v25, v25
	v_exp_f32_e32 v33, v33
	v_add_f32_e32 v3, v21, v3
	v_add_f32_e32 v4, v29, v4
	v_add_f32_e32 v3, v22, v3
	v_add_f32_e32 v4, v30, v4
	v_add_f32_e32 v3, v23, v3
	v_add_f32_e32 v4, v31, v4
	v_add_f32_e32 v3, v24, v3
	v_add_f32_e32 v4, v32, v4
	v_lshlrev_b32_e32 v35, 7, v35
	v_bitop3_b32 v38, v144, v34, 7 bitop3:0x78
	v_add_f32_e32 v3, v25, v3
	v_add_f32_e32 v4, v33, v4
	v_lshl_or_b32 v150, v38, 4, v35
	v_bitop3_b32 v38, v39, v34, 7 bitop3:0x78
	v_add_f32_e32 v3, v3, v4
	v_lshl_or_b32 v151, v38, 4, v35
	v_add_f32_e32 v152, v2, v3
	v_add_u32_e32 v2, 0, v150
	ds_read_b128 v[86:89], v2 offset:16384
	ds_read_b128 v[82:85], v2 offset:20480
	ds_read_b128 v[78:81], v2 offset:24576
	ds_read_b128 v[74:77], v2 offset:28672
	v_add_u32_e32 v2, 0, v151
	s_add_i32 s2, s18, s17
	s_mul_i32 s15, s15, 0x21000
	ds_read_b128 v[126:129], v2 offset:16384
	ds_read_b128 v[122:125], v2 offset:20480
	ds_read_b128 v[94:97], v2 offset:24576
	ds_read_b128 v[90:93], v2 offset:28672
	v_lshl_add_u64 v[136:137], s[10:11], 0, v[0:1]
	s_mov_b64 s[22:23], s[10:11]
	v_add_u32_e32 v244, 0x800, v0
	v_add_u32_e32 v245, 0x880, v0
	s_add_i32 s10, s16, 0xffffff80
	s_mul_hi_i32 s11, s2, 0x4200
	s_mulk_i32 s2, 0x4200
	v_mov_b32_e32 v0, s15
	v_mad_u32_u24 v0, v36, s65, v0
	s_add_u32 s4, s4, s2
	v_or_b32_e32 v0, v0, v37
	s_addc_u32 s5, s5, s11
	v_cvt_pk_bf16_f32 v72, v14, v15
	v_bitop3_b32 v38, v40, v34, 7 bitop3:0x78
	v_bitop3_b32 v34, v41, v34, 7 bitop3:0x78
	v_lshl_add_u64 v[2:3], s[4:5], 0, v[0:1]
	s_add_u32 s20, s4, 0x180
	s_addc_u32 s21, s5, 0
	v_mov_b32_e32 v246, v0
	v_add_u32_e32 v247, 0x108000, v0
	s_mov_b64 s[4:5], 0x108180
	v_mov_b32_e32 v14, v1
	v_mov_b32_e32 v15, v1
	v_cvt_pk_bf16_f32 v68, v6, v7
	v_cvt_pk_bf16_f32 v69, v8, v9
	v_cvt_pk_bf16_f32 v70, v10, v11
	v_cvt_pk_bf16_f32 v71, v12, v13
	v_cvt_pk_bf16_f32 v118, v18, v19
	v_cvt_pk_bf16_f32 v119, v20, v21
	v_cvt_pk_bf16_f32 v120, v22, v23
	v_cvt_pk_bf16_f32 v121, v24, v25
	v_cvt_pk_bf16_f32 v114, v26, v27
	v_cvt_pk_bf16_f32 v115, v28, v29
	v_cvt_pk_bf16_f32 v116, v30, v31
	v_cvt_pk_bf16_f32 v117, v32, v33
	v_lshl_or_b32 v149, v38, 4, v35
	v_lshl_or_b32 v146, v34, 4, v35
	v_lshl_add_u64 v[138:139], v[2:3], 0, s[4:5]
	v_mov_b32_e32 v0, v1
	v_mov_b32_e32 v2, v1
	v_mov_b32_e32 v3, v1
	v_mov_b32_e32 v4, v1
	v_mov_b32_e32 v5, v1
	v_mov_b32_e32 v6, v1
	v_mov_b32_e32 v7, v1
	v_mov_b32_e32 v8, v1
	v_mov_b32_e32 v9, v1
	v_mov_b32_e32 v10, v1
	v_mov_b32_e32 v11, v1
	v_mov_b32_e32 v12, v1
	v_mov_b32_e32 v13, v1
	v_mov_b64_e32 v[64:65], v[14:15]
	v_mov_b64_e32 v[48:49], v[14:15]
	v_mov_b64_e32 v[32:33], v[14:15]
	v_cvt_pk_bf16_f32 v73, v16, v17
	v_mov_b64_e32 v[62:63], v[12:13]
	v_mov_b64_e32 v[60:61], v[10:11]
	v_mov_b64_e32 v[58:59], v[8:9]
	v_mov_b64_e32 v[56:57], v[6:7]
	v_mov_b64_e32 v[54:55], v[4:5]
	v_mov_b64_e32 v[52:53], v[2:3]
	v_mov_b64_e32 v[50:51], v[0:1]
	v_mov_b64_e32 v[46:47], v[12:13]
	v_mov_b64_e32 v[44:45], v[10:11]
	v_mov_b64_e32 v[42:43], v[8:9]
	v_mov_b64_e32 v[40:41], v[6:7]
	v_mov_b64_e32 v[38:39], v[4:5]
	v_mov_b64_e32 v[36:37], v[2:3]
	v_mov_b64_e32 v[34:35], v[0:1]
	v_mov_b64_e32 v[30:31], v[12:13]
	v_mov_b64_e32 v[28:29], v[10:11]
	v_mov_b64_e32 v[26:27], v[8:9]
	v_mov_b64_e32 v[24:25], v[6:7]
	v_mov_b64_e32 v[22:23], v[4:5]
	v_mov_b64_e32 v[20:21], v[2:3]
	v_mov_b64_e32 v[18:19], v[0:1]
	v_mov_b64_e32 v[16:17], v[14:15]
	v_ashrrev_i32_e32 v135, 31, v134
	v_mov_b32_e32 v140, 1.0
	s_mov_b64 s[4:5], 0
	s_mov_b32 s17, 0
	v_mov_b64_e32 v[14:15], v[12:13]
	v_mov_b64_e32 v[12:13], v[10:11]
	v_mov_b64_e32 v[10:11], v[8:9]
	v_mov_b64_e32 v[8:9], v[6:7]
	v_mov_b64_e32 v[6:7], v[4:5]
	v_mov_b64_e32 v[4:5], v[2:3]
	v_mov_b64_e32 v[2:3], v[0:1]
	s_mov_b32 s11, 0
	v_mov_b32_e32 v153, 0
	s_add_i32 s18, s14, 0x8000
	v_add_u32_e32 v136, s18, v141
	v_add_u32_e32 v137, s18, v145
	v_add_u32_e32 v138, s18, v147
	v_add_u32_e32 v139, s18, v148
	v_mov_b32_e32 v248, v149
	v_mov_b32_e32 v255, v146

; #define MFMA32(a, b, c) __builtin_amdgcn_mfma_f32_32x32x16_bf16((a), (b), (c), 0, 0, 0)
; #define VLOAD(dst, sbv, q) do { _Pragma("unroll") for (int d_ = 0; d_ < 4; ++d_) dst[d_] = *(const lds_bf16x8*)((sbv) + vo[q] + d_ * 4096); } while (0)
; #define FENCE __builtin_amdgcn_sched_barrier(0)
; DI void diff_unit(KP p, int l, int b, int h, int qb, int isctx, float lamv, float lam_init, char* ldsc) {
;     ...
;     const lds_u8* sbv = L + stg * STG + 16384;
;     const lds_u8* sbk = L + stg1 * STG + comp * 8192;
;     bf16x8 kf[2][4];
;     f32x16 st[2];
; #pragma unroll
;     for (int t = 0; t < 2; ++t)
; #pragma unroll
;       for (int ks = 0; ks < 4; ++ks) kf[t][ks] = *(const lds_bf16x8*)(sbk + ko[ks] + t * 4096);
;     FENCE;
;     pv_grp(o, vA, P[0]); pv_grp(o, vB, P[1]);
;     VLOAD(vA, sbv, 2); VLOAD(vB, sbv, 3);
;     FENCE;
; #pragma unroll
;     for (int i = 0; i < 16; ++i) { st[0][i] = 0.f; st[1][i] = 0.f; }
; #pragma unroll
;     for (int ks = 0; ks < 4; ++ks) st[0] = MFMA32(kf[0][ks], qf[ks], st[0]);
; #pragma unroll
;     for (int ks = 0; ks < 4; ++ks) st[1] = MFMA32(kf[1][ks], qf[ks], st[1]);
;     FENCE;
;     pv_grp(o, vA, P[2]);
;     const float mx = tile_max(st);
;     need = !__all(mx <= m + 8.0f);
;     const float mn = need ? fmaxf(m, mx) : m;
;     alpha = __builtin_amdgcn_exp2f(m - mn);
;     FENCE;
;     ...
;     { const lds_u8* sbn = L + stg1 * STG + 16384; VLOAD(vA, sbn, 0); VLOAD(vB, sbn, 1); }
.LBB0_477:
	s_add_i32 s2, s17, 1
	s_and_b32 s16, s2, 3
	s_lshl_b32 s2, s16, 15
	s_add_i32 s15, s2, 0
	ds_read_b128 v[154:157], v136
	ds_read_b128 v[192:195], v136 offset:4096
	ds_read_b128 v[196:199], v137
	ds_read_b128 v[200:203], v137 offset:4096
	ds_read_b128 v[204:207], v138
	ds_read_b128 v[208:211], v138 offset:4096
	ds_read_b128 v[212:215], v139
	ds_read_b128 v[216:219], v139 offset:4096
	s_waitcnt lgkmcnt(8)
	v_mfma_f32_32x32x16_bf16 v[50:65], v[86:89], v[66:69], v[50:65]
	ds_read_b128 v[220:223], v248 offset:24576
	ds_read_b128 v[224:227], v248 offset:28672
	s_add_i32 s18, s3, 0xc0
	s_add_i32 s19, s10, 64
	s_cmp_eq_u32 s11, 0
	s_cselect_b32 s19, s18, s19
	s_mul_i32 s19, s19, 0x1600
	s_add_u32 s18, s22, s19
	s_addc_u32 s19, s23, 0
	s_add_i32 s24, s17, 3
	s_and_b32 s24, s24, 3
	s_lshl_b32 s24, s24, 15
	s_add_i32 s24, s13, s24
	s_mov_b32 m0, s24
	v_mfma_f32_32x32x16_bf16 v[34:49], v[82:85], v[66:69], v[34:49]
	global_load_lds_dwordx4 v244, s[18:19]
	s_add_i32 m0, s24, 0x2000
	v_mfma_f32_32x32x16_bf16 v[18:33], v[78:81], v[66:69], v[18:33]
	v_mfma_f32_32x32x16_bf16 v[2:17], v[74:77], v[66:69], v[2:17]
	v_mov_b64_e32 v[66:67], v[252:253]
	v_mov_b64_e32 v[68:69], v[252:253]
	v_mov_b64_e32 v[74:75], v[252:253]
	global_load_lds_dwordx4 v245, s[18:19]
	s_add_i32 m0, s24, 0x4000
	v_mfma_f32_32x32x16_bf16 v[50:65], v[126:129], v[70:73], v[50:65]
	v_mov_b64_e32 v[76:77], v[252:253]
	v_mov_b64_e32 v[78:79], v[252:253]
	v_mov_b64_e32 v[80:81], v[252:253]
	ds_read_b128 v[126:129], v248 offset:20480
	v_mfma_f32_32x32x16_bf16 v[34:49], v[122:125], v[70:73], v[34:49]
	v_mov_b64_e32 v[82:83], v[252:253]
	v_mov_b64_e32 v[84:85], v[252:253]
	ds_read_b128 v[122:125], v248 offset:16384
	ds_read_b128 v[228:231], v255 offset:16384
	ds_read_b128 v[232:235], v255 offset:20480
	ds_read_b128 v[236:239], v255 offset:24576
	ds_read_b128 v[240:243], v255 offset:28672
	v_mfma_f32_32x32x16_bf16 v[18:33], v[94:97], v[70:73], v[18:33]
	v_mov_b64_e32 v[86:87], v[252:253]
	v_mov_b64_e32 v[88:89], v[252:253]
	v_mov_b64_e32 v[94:95], v[252:253]
	v_mov_b64_e32 v[96:97], v[252:253]
	v_mfma_f32_32x32x16_bf16 v[2:17], v[90:93], v[70:73], v[2:17]
	v_mov_b64_e32 v[70:71], v[252:253]
	v_mov_b64_e32 v[72:73], v[252:253]
	v_mov_b64_e32 v[90:91], v[252:253]
	v_mov_b64_e32 v[92:93], v[252:253]
	global_load_lds_dwordx4 v246, s[20:21]
	s_add_i32 m0, s24, 0x6000
	s_waitcnt lgkmcnt(8)
	v_mfma_f32_32x32x16_bf16 v[66:81], v[192:195], v[98:101], v[66:81]
	v_mfma_f32_32x32x16_bf16 v[82:97], v[154:157], v[98:101], v[82:97]
	v_mfma_f32_32x32x16_bf16 v[66:81], v[200:203], v[102:105], v[66:81]
	v_mfma_f32_32x32x16_bf16 v[82:97], v[196:199], v[102:105], v[82:97]
	global_load_lds_dwordx4 v247, s[20:21]
	s_add_u32 s20, s20, 0x80
	s_addc_u32 s21, s21, 0
	v_mfma_f32_32x32x16_bf16 v[66:81], v[208:211], v[106:109], v[66:81]
	v_mfma_f32_32x32x16_bf16 v[82:97], v[204:207], v[106:109], v[82:97]
	v_mfma_f32_32x32x16_bf16 v[66:81], v[216:219], v[110:113], v[66:81]
	v_mfma_f32_32x32x16_bf16 v[82:97], v[212:215], v[110:113], v[82:97]
	s_waitcnt lgkmcnt(0)
	v_mfma_f32_32x32x16_bf16 v[50:65], v[122:125], v[118:121], v[50:65]
	v_add_u32_e32 v251, s15, v150
	v_add_u32_e32 v249, s15, v151
	s_add_i32 s18, s16, 1
	s_and_b32 s18, s18, 3
	s_lshl_b32 s18, s18, 15
	s_add_i32 s18, s18, s14
	v_add_u32_e32 v136, s18, v141
	v_add_u32_e32 v137, s18, v145
	v_add_u32_e32 v138, s18, v147
	v_add_u32_e32 v139, s18, v148
	s_lshl_b32 s19, s16, 15
	v_add_u32_e32 v248, s19, v149
	v_add_u32_e32 v255, s19, v146
	s_nop 0
	v_max3_f32 v0, v82, v83, v84
	v_max3_f32 v250, v66, v67, v68
	v_mfma_f32_32x32x16_bf16 v[34:49], v[126:129], v[118:121], v[34:49]
	v_max3_f32 v0, v0, v85, v86
	v_max3_f32 v250, v250, v69, v70
	v_max3_f32 v0, v0, v87, v88
	v_max3_f32 v250, v250, v71, v72
	v_max3_f32 v0, v0, v89, v90
	v_mfma_f32_32x32x16_bf16 v[18:33], v[220:223], v[118:121], v[18:33]
	v_max3_f32 v250, v250, v73, v74
	v_max3_f32 v0, v0, v91, v92
	v_max3_f32 v250, v250, v75, v76
	v_max3_f32 v0, v0, v93, v94
	v_max3_f32 v250, v250, v77, v78
	v_mfma_f32_32x32x16_bf16 v[2:17], v[224:227], v[118:121], v[2:17]
	v_max3_f32 v0, v0, v95, v96
	v_max3_f32 v250, v250, v79, v80
	v_max_f32_e32 v0, v0, v97
	v_max_f32_e32 v250, v250, v81
	v_max_f32_e32 v0, v0, v250
	v_mov_b32_e32 v118, v0
	s_nop 1
	v_permlane32_swap_b32_e32 v0, v118
	v_max_f32_e32 v0, v0, v118
	v_cmp_ge_f32_e32 vcc, 0x41000000, v0
	s_cmp_lg_u64 vcc, exec
	s_cselect_b64 s[4:5], -1, 0
	s_cbranch_scc0 .Ldiff_nosub
	v_max_f32_e32 v0, 0, v0
	v_sub_f32_e32 v252, v252, v0
	v_exp_f32_e64 v140, -v0
	v_mov_b32_e32 v253, v252
	v_pk_mul_f32 v[152:153], v[152:153], v[140:141] op_sel_hi:[1,0]
	v_sub_f32_e32 v82, v82, v0
	v_sub_f32_e32 v83, v83, v0
	v_sub_f32_e32 v84, v84, v0
	v_sub_f32_e32 v85, v85, v0
	v_sub_f32_e32 v86, v86, v0
	v_sub_f32_e32 v87, v87, v0
	v_sub_f32_e32 v88, v88, v0
	v_sub_f32_e32 v89, v89, v0
	v_sub_f32_e32 v90, v90, v0
	v_sub_f32_e32 v91, v91, v0
	v_sub_f32_e32 v92, v92, v0
	v_sub_f32_e32 v93, v93, v0
	v_sub_f32_e32 v94, v94, v0
	v_sub_f32_e32 v95, v95, v0
	v_sub_f32_e32 v96, v96, v0
	v_sub_f32_e32 v97, v97, v0
	v_sub_f32_e32 v66, v66, v0
	v_sub_f32_e32 v67, v67, v0
	v_sub_f32_e32 v68, v68, v0
	v_sub_f32_e32 v69, v69, v0
	v_sub_f32_e32 v70, v70, v0
	v_sub_f32_e32 v71, v71, v0
	v_sub_f32_e32 v72, v72, v0
	v_sub_f32_e32 v73, v73, v0
	v_sub_f32_e32 v74, v74, v0
	v_sub_f32_e32 v75, v75, v0
	v_sub_f32_e32 v76, v76, v0
	v_sub_f32_e32 v77, v77, v0
	v_sub_f32_e32 v78, v78, v0
	v_sub_f32_e32 v79, v79, v0
	v_sub_f32_e32 v80, v80, v0
	v_sub_f32_e32 v81, v81, v0

; __global__ void __launch_bounds__(512) mega(Params pv) {
;   extern __shared__ __attribute__((aligned(16))) char lds[];
	.amdhsa_kernel _Z4mega6Params
		.amdhsa_group_segment_fixed_size 0
		.amdhsa_private_segment_fixed_size 0
		.amdhsa_kernarg_size 576
		.amdhsa_user_sgpr_count 2
		.amdhsa_user_sgpr_dispatch_ptr 0
		.amdhsa_user_sgpr_queue_ptr 0
		.amdhsa_user_sgpr_kernarg_segment_ptr 1
		.amdhsa_user_sgpr_dispatch_id 0
		.amdhsa_user_sgpr_kernarg_preload_length 0
		.amdhsa_user_sgpr_kernarg_preload_offset 0
		.amdhsa_user_sgpr_private_segment_size 0
		.amdhsa_uses_dynamic_stack 0
		.amdhsa_enable_private_segment 0
		.amdhsa_system_sgpr_workgroup_id_x 1
		.amdhsa_system_sgpr_workgroup_id_y 0
		.amdhsa_system_sgpr_workgroup_id_z 0
		.amdhsa_system_sgpr_workgroup_info 0
		.amdhsa_system_vgpr_workitem_id 2
		.amdhsa_next_free_vgpr 256
		.amdhsa_next_free_sgpr 100
		.amdhsa_accum_offset 256
		.amdhsa_reserve_vcc 1
		.amdhsa_float_round_mode_32 0
		.amdhsa_float_round_mode_16_64 0
		.amdhsa_float_denorm_mode_32 3
		.amdhsa_float_denorm_mode_16_64 3
		.amdhsa_dx10_clamp 1
		.amdhsa_ieee_mode 1
		.amdhsa_fp16_overflow 0
		.amdhsa_tg_split 0
		.amdhsa_exception_fp_ieee_invalid_op 0
		.amdhsa_exception_fp_denorm_src 0
		.amdhsa_exception_fp_ieee_div_zero 0
		.amdhsa_exception_fp_ieee_overflow 0
		.amdhsa_exception_fp_ieee_underflow 0
		.amdhsa_exception_fp_ieee_inexact 0
		.amdhsa_exception_int_div_zero 0
	.end_amdhsa_kernel

; __global__ void __launch_bounds__(512) mega(Params pv) {
;   extern __shared__ __attribute__((aligned(16))) char lds[];
amdhsa.kernels:
  - .agpr_count:     0
    .args:
      - .offset:         0
        .size:           320
        .value_kind:     by_value
      - .offset:         320
        .size:           4
        .value_kind:     hidden_block_count_x
      - .offset:         324
        .size:           4
        .value_kind:     hidden_block_count_y
      - .offset:         328
        .size:           4
        .value_kind:     hidden_block_count_z
      - .offset:         332
        .size:           2
        .value_kind:     hidden_group_size_x
      - .offset:         334
        .size:           2
        .value_kind:     hidden_group_size_y
      - .offset:         336
        .size:           2
        .value_kind:     hidden_group_size_z
      - .offset:         338
        .size:           2
        .value_kind:     hidden_remainder_x
      - .offset:         340
        .size:           2
        .value_kind:     hidden_remainder_y
      - .offset:         342
        .size:           2
        .value_kind:     hidden_remainder_z
      - .offset:         360
        .size:           8
        .value_kind:     hidden_global_offset_x
      - .offset:         368
        .size:           8
        .value_kind:     hidden_global_offset_y
      - .offset:         376
        .size:           8
        .value_kind:     hidden_global_offset_z
      - .offset:         384
        .size:           2
        .value_kind:     hidden_grid_dims
      - .offset:         408
        .size:           8
        .value_kind:     hidden_multigrid_sync_arg
      - .offset:         440
        .size:           4
        .value_kind:     hidden_dynamic_lds_size
    .group_segment_fixed_size: 0
    .kernarg_segment_align: 8
    .kernarg_segment_size: 576
    .language:       OpenCL C
    .language_version:
      - 2
      - 0
    .max_flat_workgroup_size: 512
    .name:           _Z4mega6Params
    .private_segment_fixed_size: 0
    .sgpr_count:     106
    .sgpr_spill_count: 28
    .symbol:         _Z4mega6Params.kd
    .uniform_work_group_size: 1
    .uses_dynamic_stack: false
    .vgpr_count:     256
    .vgpr_spill_count: 0
    .wavefront_size: 64
